# v84 + attention: next K/V tile staged to the other LDS buffer between softmax and PV, padded to keep all later code's byte placement
# baseline (speedup 1.0000x reference)
.LBB0_352:
	v_readlane_b32 s84, v254, 40
	v_readlane_b32 s88, v254, 49
	v_readlane_b32 s86, v254, 38
	v_readlane_b32 s94, v254, 34
	v_readlane_b32 s4, v254, 32
	v_readlane_b32 s81, v255, 5
	v_readlane_b32 s85, v254, 41
	v_readlane_b32 s89, v254, 50
	v_readlane_b32 s90, v254, 51
	v_readlane_b32 s91, v254, 52
	v_readlane_b32 s87, v254, 39
	v_readlane_b32 s92, v254, 37
	v_readlane_b32 s93, v254, 36
	v_readlane_b32 s95, v254, 35
	v_readlane_b32 s5, v254, 33
	s_nop 0
